# norm_phase parameter-load hoist + pre_phase mu1 loads issued with mu0 loads
# speedup vs baseline: 1.0126x; 1.0030x over previous
.LBB0_958:
	s_or_b64 exec, exec, s[26:27]
	v_ashrrev_i32_e32 v39, 31, v38
	v_lshlrev_b64 v[40:41], 2, v[38:39]
	v_lshl_add_u64 v[58:59], s[50:51], 0, v[40:41]
	global_load_dwordx4 v[54:57], v[58:59], off offset:16
	s_nop 0
	global_load_dwordx4 v[58:61], v[58:59], off
	v_lshl_add_u64 v[98:99], s[52:53], 0, v[40:41]
	global_load_dwordx4 v[74:77], v[98:99], off offset:16
	global_load_dwordx4 v[78:81], v[98:99], off
	v_add_u32_e32 v42, s13, v52
	v_cmp_lt_i32_e32 vcc, s30, v42
	s_waitcnt vmcnt(12)
	v_lshlrev_b32_e32 v70, 16, v26
	v_and_b32_e32 v71, 0xffff0000, v26
	v_cndmask_b32_e64 v44, 0, 1.0, vcc
	s_waitcnt vmcnt(11)
	v_lshlrev_b32_e32 v62, 16, v30
	v_and_b32_e32 v63, 0xffff0000, v30
	v_lshl_add_u64 v[40:41], s[52:53], 0, v[40:41]
	v_pk_fma_f32 v[62:63], v[44:45], v[62:63], v[70:71] op_sel_hi:[0,1,1] neg_lo:[0,0,1] neg_hi:[0,0,1]
	v_cmp_gt_i32_e32 vcc, s36, v42
	v_lshlrev_b32_e32 v26, 16, v27
	v_and_b32_e32 v27, 0xffff0000, v27
	v_lshlrev_b32_e32 v30, 16, v31
	v_and_b32_e32 v31, 0xffff0000, v31
	v_cndmask_b32_e64 v0, 0, 1.0, vcc
	s_waitcnt vmcnt(10)
	v_lshlrev_b32_e32 v72, 16, v34
	v_and_b32_e32 v73, 0xffff0000, v34
	v_lshlrev_b32_e32 v34, 16, v35
	v_and_b32_e32 v35, 0xffff0000, v35
	v_pk_fma_f32 v[30:31], v[44:45], v[30:31], v[26:27] op_sel_hi:[0,1,1] neg_lo:[0,0,1] neg_hi:[0,0,1]
	v_ashrrev_i32_e32 v43, 31, v42
	s_movk_i32 s26, 0x17f
	v_cmp_lt_i32_e32 vcc, s26, v38
	s_waitcnt vmcnt(2)
	v_pk_fma_f32 v[58:59], v[58:59], v[62:63], v[70:71]
	v_pk_fma_f32 v[30:31], v[30:31], v[60:61], v[26:27]
	v_pk_fma_f32 v[26:27], v[0:1], v[34:35], v[26:27] op_sel_hi:[0,1,1] neg_lo:[0,0,1] neg_hi:[0,0,1]
	v_pk_fma_f32 v[40:41], v[0:1], v[72:73], v[70:71] op_sel_hi:[0,1,1] neg_lo:[0,0,1] neg_hi:[0,0,1]
	s_waitcnt vmcnt(0)
	v_pk_fma_f32 v[34:35], v[26:27], v[80:81], v[30:31]
	v_lshlrev_b32_e32 v26, 16, v28
	v_and_b32_e32 v27, 0xffff0000, v28
	v_lshlrev_b32_e32 v30, 16, v32
	v_and_b32_e32 v31, 0xffff0000, v32
	v_pk_fma_f32 v[40:41], v[78:79], v[40:41], v[58:59]
	v_lshlrev_b32_e32 v58, 16, v36
	v_and_b32_e32 v59, 0xffff0000, v36
	v_pk_fma_f32 v[30:31], v[44:45], v[30:31], v[26:27] op_sel_hi:[0,1,1] neg_lo:[0,0,1] neg_hi:[0,0,1]
	v_pk_fma_f32 v[30:31], v[30:31], v[54:55], v[26:27]
	v_pk_fma_f32 v[26:27], v[0:1], v[58:59], v[26:27] op_sel_hi:[0,1,1] neg_lo:[0,0,1] neg_hi:[0,0,1]
	v_pk_fma_f32 v[30:31], v[26:27], v[74:75], v[30:31]
	v_lshlrev_b32_e32 v26, 16, v29
	v_and_b32_e32 v27, 0xffff0000, v29
	v_lshlrev_b32_e32 v28, 16, v33
	v_and_b32_e32 v29, 0xffff0000, v33
	v_lshlrev_b32_e32 v32, 16, v37
	v_and_b32_e32 v33, 0xffff0000, v37
	v_pk_fma_f32 v[28:29], v[44:45], v[28:29], v[26:27] op_sel_hi:[0,1,1] neg_lo:[0,0,1] neg_hi:[0,0,1]
	v_pk_fma_f32 v[28:29], v[28:29], v[56:57], v[26:27]
	v_pk_fma_f32 v[26:27], v[0:1], v[32:33], v[26:27] op_sel_hi:[0,1,1] neg_lo:[0,0,1] neg_hi:[0,0,1]
	v_pk_fma_f32 v[28:29], v[26:27], v[76:77], v[28:29]
	v_lshl_add_u64 v[26:27], s[56:57], 0, v[42:43]
	s_and_saveexec_b64 s[26:27], vcc
	s_xor_b64 s[48:49], exec, s[26:27]
	s_cbranch_execz .LBB0_976
	v_cmp_lt_u32_e32 vcc, s88, v38
	s_and_saveexec_b64 s[26:27], vcc
	s_xor_b64 s[60:61], exec, s[26:27]
	s_cbranch_execz .LBB0_973
	s_movk_i32 s26, 0x47f
	v_cmp_lt_u32_e32 vcc, s26, v38
	s_and_saveexec_b64 s[26:27], vcc
	s_xor_b64 s[62:63], exec, s[26:27]
	s_cbranch_execz .LBB0_970
	s_movk_i32 s26, 0x4bf
	v_cmp_lt_u32_e32 vcc, s26, v38
	s_and_saveexec_b64 s[26:27], vcc
	s_xor_b64 s[26:27], exec, s[26:27]
	s_cbranch_execz .LBB0_967
	s_movk_i32 s28, 0x4ff
	v_cmp_lt_u32_e32 vcc, s28, v38
	s_and_saveexec_b64 s[28:29], vcc
	s_xor_b64 s[64:65], exec, s[28:29]
	s_cbranch_execz .LBB0_964
	v_mul_f32_e32 v30, 0xbfb8aa3b, v30
	v_mul_f32_e32 v31, 0xbfb8aa3b, v31
	v_mul_f32_e32 v28, 0xbfb8aa3b, v28
	v_mul_f32_e32 v0, 0xbfb8aa3b, v40
	v_mul_f32_e32 v32, 0xbfb8aa3b, v41
	v_mul_f32_e32 v33, 0xbfb8aa3b, v34
	v_mul_f32_e32 v34, 0xbfb8aa3b, v35
	v_exp_f32_e32 v30, v30
	v_exp_f32_e32 v31, v31
	v_exp_f32_e32 v28, v28
	v_mul_f32_e32 v29, 0xbfb8aa3b, v29
	v_exp_f32_e32 v0, v0
	v_exp_f32_e32 v32, v32
	v_exp_f32_e32 v33, v33
	v_exp_f32_e32 v34, v34
	v_exp_f32_e32 v29, v29
	v_add_f32_e32 v30, 1.0, v30
	v_add_f32_e32 v31, 1.0, v31
	v_add_f32_e32 v28, 1.0, v28
	v_lshlrev_b64 v[26:27], 9, v[26:27]
	v_add_f32_e32 v0, 1.0, v0
	v_add_f32_e32 v32, 1.0, v32
	v_add_f32_e32 v33, 1.0, v33
	v_add_f32_e32 v34, 1.0, v34
	v_rcp_f32_e32 v30, v30
	v_rcp_f32_e32 v31, v31
	v_rcp_f32_e32 v35, v28
	v_add_f32_e32 v28, 1.0, v29
	v_lshl_add_u64 v[26:27], s[14:15], 0, v[26:27]
	v_rcp_f32_e32 v0, v0
	v_rcp_f32_e32 v32, v32
	v_rcp_f32_e32 v33, v33
	v_rcp_f32_e32 v34, v34
	v_rcp_f32_e32 v36, v28
	v_cvt_pk_bf16_f32 v28, v0, v32
	v_cvt_pk_bf16_f32 v29, v33, v34
	v_cvt_pk_bf16_f32 v30, v30, v31
	v_cvt_pk_bf16_f32 v31, v35, v36
	v_lshl_add_u64 v[26:27], v[38:39], 1, v[26:27]
	global_store_dwordx4 v[26:27], v[28:31], off offset:-2304

.LBB0_987:
	s_or_b64 exec, exec, s[26:27]
	s_waitcnt vmcnt(8)
	v_ashrrev_i32_e32 v27, 31, v26
	v_lshlrev_b64 v[28:29], 2, v[26:27]
	v_lshl_add_u64 v[38:39], s[50:51], 0, v[28:29]
	global_load_dwordx4 v[34:37], v[38:39], off offset:16
	s_nop 0
	global_load_dwordx4 v[38:41], v[38:39], off
	v_lshl_add_u64 v[100:101], s[52:53], 0, v[28:29]
	global_load_dwordx4 v[82:85], v[100:101], off offset:16
	global_load_dwordx4 v[86:89], v[100:101], off
	s_waitcnt vmcnt(11)
	v_add_u32_e32 v30, s13, v33
	v_cmp_lt_i32_e32 vcc, s30, v30
	s_waitcnt vmcnt(9)
	v_lshlrev_b32_e32 v42, 16, v14
	v_and_b32_e32 v43, 0xffff0000, v14
	v_cndmask_b32_e64 v32, 0, 1.0, vcc
	s_waitcnt vmcnt(8)
	v_lshlrev_b32_e32 v52, 16, v18
	v_and_b32_e32 v53, 0xffff0000, v18
	v_lshl_add_u64 v[28:29], s[52:53], 0, v[28:29]
	v_pk_fma_f32 v[52:53], v[32:33], v[52:53], v[42:43] op_sel_hi:[0,1,1] neg_lo:[0,0,1] neg_hi:[0,0,1]
	v_cmp_gt_i32_e32 vcc, s36, v30
	v_lshlrev_b32_e32 v14, 16, v15
	v_and_b32_e32 v15, 0xffff0000, v15
	v_lshlrev_b32_e32 v18, 16, v19
	v_and_b32_e32 v19, 0xffff0000, v19
	v_cndmask_b32_e64 v0, 0, 1.0, vcc
	s_waitcnt vmcnt(7)
	v_lshlrev_b32_e32 v60, 16, v22
	v_and_b32_e32 v61, 0xffff0000, v22
	v_lshlrev_b32_e32 v22, 16, v23
	v_and_b32_e32 v23, 0xffff0000, v23
	v_pk_fma_f32 v[18:19], v[32:33], v[18:19], v[14:15] op_sel_hi:[0,1,1] neg_lo:[0,0,1] neg_hi:[0,0,1]
	v_ashrrev_i32_e32 v31, 31, v30
	s_movk_i32 s26, 0x17f
	v_cmp_lt_i32_e32 vcc, s26, v26
	s_waitcnt vmcnt(2)
	v_pk_fma_f32 v[38:39], v[38:39], v[52:53], v[42:43]
	v_pk_fma_f32 v[18:19], v[18:19], v[40:41], v[14:15]
	v_pk_fma_f32 v[14:15], v[0:1], v[22:23], v[14:15] op_sel_hi:[0,1,1] neg_lo:[0,0,1] neg_hi:[0,0,1]
	v_pk_fma_f32 v[28:29], v[0:1], v[60:61], v[42:43] op_sel_hi:[0,1,1] neg_lo:[0,0,1] neg_hi:[0,0,1]
	s_waitcnt vmcnt(0)
	v_pk_fma_f32 v[22:23], v[14:15], v[88:89], v[18:19]
	v_lshlrev_b32_e32 v14, 16, v16
	v_and_b32_e32 v15, 0xffff0000, v16
	v_lshlrev_b32_e32 v18, 16, v20
	v_and_b32_e32 v19, 0xffff0000, v20
	v_pk_fma_f32 v[28:29], v[86:87], v[28:29], v[38:39]
	v_lshlrev_b32_e32 v38, 16, v24
	v_and_b32_e32 v39, 0xffff0000, v24
	v_pk_fma_f32 v[18:19], v[32:33], v[18:19], v[14:15] op_sel_hi:[0,1,1] neg_lo:[0,0,1] neg_hi:[0,0,1]
	v_pk_fma_f32 v[18:19], v[18:19], v[34:35], v[14:15]
	v_pk_fma_f32 v[14:15], v[0:1], v[38:39], v[14:15] op_sel_hi:[0,1,1] neg_lo:[0,0,1] neg_hi:[0,0,1]
	v_pk_fma_f32 v[18:19], v[14:15], v[82:83], v[18:19]
	v_lshlrev_b32_e32 v14, 16, v17
	v_and_b32_e32 v15, 0xffff0000, v17
	v_lshlrev_b32_e32 v16, 16, v21
	v_and_b32_e32 v17, 0xffff0000, v21
	v_lshlrev_b32_e32 v20, 16, v25
	v_and_b32_e32 v21, 0xffff0000, v25
	v_pk_fma_f32 v[16:17], v[32:33], v[16:17], v[14:15] op_sel_hi:[0,1,1] neg_lo:[0,0,1] neg_hi:[0,0,1]
	v_pk_fma_f32 v[16:17], v[16:17], v[36:37], v[14:15]
	v_pk_fma_f32 v[14:15], v[0:1], v[20:21], v[14:15] op_sel_hi:[0,1,1] neg_lo:[0,0,1] neg_hi:[0,0,1]
	v_pk_fma_f32 v[16:17], v[14:15], v[84:85], v[16:17]
	v_lshl_add_u64 v[14:15], s[56:57], 0, v[30:31]
	s_and_saveexec_b64 s[26:27], vcc
	s_xor_b64 s[46:47], exec, s[26:27]
	s_cbranch_execz .LBB0_1005
	v_cmp_lt_u32_e32 vcc, s88, v26
	s_and_saveexec_b64 s[26:27], vcc
	s_xor_b64 s[58:59], exec, s[26:27]
	s_cbranch_execz .LBB0_1002
	s_movk_i32 s26, 0x47f
	v_cmp_lt_u32_e32 vcc, s26, v26
	s_and_saveexec_b64 s[26:27], vcc
	s_xor_b64 s[60:61], exec, s[26:27]
	s_cbranch_execz .LBB0_999
	s_movk_i32 s26, 0x4bf
	v_cmp_lt_u32_e32 vcc, s26, v26
	s_and_saveexec_b64 s[26:27], vcc
	s_xor_b64 s[26:27], exec, s[26:27]
	s_cbranch_execz .LBB0_996
	s_movk_i32 s28, 0x4ff
	v_cmp_lt_u32_e32 vcc, s28, v26
	s_and_saveexec_b64 s[28:29], vcc
	s_xor_b64 s[62:63], exec, s[28:29]
	s_cbranch_execz .LBB0_993
	v_mul_f32_e32 v18, 0xbfb8aa3b, v18
	v_mul_f32_e32 v19, 0xbfb8aa3b, v19
	v_mul_f32_e32 v16, 0xbfb8aa3b, v16
	v_mul_f32_e32 v0, 0xbfb8aa3b, v28
	v_mul_f32_e32 v20, 0xbfb8aa3b, v29
	v_mul_f32_e32 v21, 0xbfb8aa3b, v22
	v_mul_f32_e32 v22, 0xbfb8aa3b, v23
	v_exp_f32_e32 v18, v18
	v_exp_f32_e32 v19, v19
	v_exp_f32_e32 v16, v16
	v_mul_f32_e32 v17, 0xbfb8aa3b, v17
	v_exp_f32_e32 v0, v0
	v_exp_f32_e32 v20, v20
	v_exp_f32_e32 v21, v21
	v_exp_f32_e32 v22, v22
	v_exp_f32_e32 v17, v17
	v_add_f32_e32 v18, 1.0, v18
	v_add_f32_e32 v19, 1.0, v19
	v_add_f32_e32 v16, 1.0, v16
	v_lshlrev_b64 v[14:15], 9, v[14:15]
	v_add_f32_e32 v0, 1.0, v0
	v_add_f32_e32 v20, 1.0, v20
	v_add_f32_e32 v21, 1.0, v21
	v_add_f32_e32 v22, 1.0, v22
	v_rcp_f32_e32 v18, v18
	v_rcp_f32_e32 v19, v19
	v_rcp_f32_e32 v23, v16
	v_add_f32_e32 v16, 1.0, v17
	v_lshl_add_u64 v[14:15], s[14:15], 0, v[14:15]
	v_rcp_f32_e32 v0, v0
	v_rcp_f32_e32 v20, v20
	v_rcp_f32_e32 v21, v21
	v_rcp_f32_e32 v22, v22
	v_rcp_f32_e32 v24, v16
	v_cvt_pk_bf16_f32 v16, v0, v20
	v_cvt_pk_bf16_f32 v17, v21, v22
	v_cvt_pk_bf16_f32 v18, v18, v19
	v_cvt_pk_bf16_f32 v19, v23, v24
	v_lshl_add_u64 v[14:15], v[26:27], 1, v[14:15]
	global_store_dwordx4 v[14:15], v[16:19], off offset:-2304

.LBB0_1016:
	s_or_b64 exec, exec, s[26:27]
	s_waitcnt vmcnt(5)
	v_ashrrev_i32_e32 v15, 31, v14
	v_lshlrev_b64 v[16:17], 2, v[14:15]
	v_lshl_add_u64 v[26:27], s[50:51], 0, v[16:17]
	global_load_dwordx4 v[22:25], v[26:27], off offset:16
	s_nop 0
	global_load_dwordx4 v[26:29], v[26:27], off
	v_lshl_add_u64 v[102:103], s[52:53], 0, v[16:17]
	global_load_dwordx4 v[90:93], v[102:103], off offset:16
	global_load_dwordx4 v[94:97], v[102:103], off
	s_waitcnt vmcnt(8)
	v_add_u32_e32 v18, s13, v21
	v_cmp_lt_i32_e32 vcc, s30, v18
	s_waitcnt vmcnt(6)
	v_lshlrev_b32_e32 v38, 16, v2
	v_and_b32_e32 v39, 0xffff0000, v2
	v_cndmask_b32_e64 v20, 0, 1.0, vcc
	s_waitcnt vmcnt(5)
	v_lshlrev_b32_e32 v30, 16, v6
	v_and_b32_e32 v31, 0xffff0000, v6
	v_lshl_add_u64 v[16:17], s[52:53], 0, v[16:17]
	v_pk_fma_f32 v[30:31], v[20:21], v[30:31], v[38:39] op_sel_hi:[0,1,1] neg_lo:[0,0,1] neg_hi:[0,0,1]
	v_cmp_gt_i32_e32 vcc, s36, v18
	v_lshlrev_b32_e32 v2, 16, v3
	v_and_b32_e32 v3, 0xffff0000, v3
	v_lshlrev_b32_e32 v6, 16, v7
	v_and_b32_e32 v7, 0xffff0000, v7
	v_cndmask_b32_e64 v0, 0, 1.0, vcc
	s_waitcnt vmcnt(4)
	v_lshlrev_b32_e32 v40, 16, v10
	v_and_b32_e32 v41, 0xffff0000, v10
	v_lshlrev_b32_e32 v10, 16, v11
	v_and_b32_e32 v11, 0xffff0000, v11
	v_pk_fma_f32 v[6:7], v[20:21], v[6:7], v[2:3] op_sel_hi:[0,1,1] neg_lo:[0,0,1] neg_hi:[0,0,1]
	v_ashrrev_i32_e32 v19, 31, v18
	s_movk_i32 s26, 0x17f
	v_cmp_lt_i32_e32 vcc, s26, v14
	s_waitcnt vmcnt(2)
	v_pk_fma_f32 v[26:27], v[26:27], v[30:31], v[38:39]
	v_pk_fma_f32 v[6:7], v[6:7], v[28:29], v[2:3]
	v_pk_fma_f32 v[2:3], v[0:1], v[10:11], v[2:3] op_sel_hi:[0,1,1] neg_lo:[0,0,1] neg_hi:[0,0,1]
	v_pk_fma_f32 v[16:17], v[0:1], v[40:41], v[38:39] op_sel_hi:[0,1,1] neg_lo:[0,0,1] neg_hi:[0,0,1]
	s_waitcnt vmcnt(0)
	v_pk_fma_f32 v[10:11], v[2:3], v[96:97], v[6:7]
	v_lshlrev_b32_e32 v2, 16, v4
	v_and_b32_e32 v3, 0xffff0000, v4
	v_lshlrev_b32_e32 v6, 16, v8
	v_and_b32_e32 v7, 0xffff0000, v8
	v_pk_fma_f32 v[16:17], v[94:95], v[16:17], v[26:27]
	v_lshlrev_b32_e32 v26, 16, v12
	v_and_b32_e32 v27, 0xffff0000, v12
	v_pk_fma_f32 v[6:7], v[20:21], v[6:7], v[2:3] op_sel_hi:[0,1,1] neg_lo:[0,0,1] neg_hi:[0,0,1]
	v_pk_fma_f32 v[6:7], v[6:7], v[22:23], v[2:3]
	v_pk_fma_f32 v[2:3], v[0:1], v[26:27], v[2:3] op_sel_hi:[0,1,1] neg_lo:[0,0,1] neg_hi:[0,0,1]
	v_pk_fma_f32 v[6:7], v[2:3], v[90:91], v[6:7]
	v_lshlrev_b32_e32 v2, 16, v5
	v_and_b32_e32 v3, 0xffff0000, v5
	v_lshlrev_b32_e32 v4, 16, v9
	v_and_b32_e32 v5, 0xffff0000, v9
	v_lshlrev_b32_e32 v8, 16, v13
	v_and_b32_e32 v9, 0xffff0000, v13
	v_pk_fma_f32 v[4:5], v[20:21], v[4:5], v[2:3] op_sel_hi:[0,1,1] neg_lo:[0,0,1] neg_hi:[0,0,1]
	v_pk_fma_f32 v[4:5], v[4:5], v[24:25], v[2:3]
	v_pk_fma_f32 v[2:3], v[0:1], v[8:9], v[2:3] op_sel_hi:[0,1,1] neg_lo:[0,0,1] neg_hi:[0,0,1]
	v_pk_fma_f32 v[4:5], v[2:3], v[92:93], v[4:5]
	v_lshl_add_u64 v[2:3], s[56:57], 0, v[18:19]
	s_and_saveexec_b64 s[26:27], vcc
	s_xor_b64 s[44:45], exec, s[26:27]
	s_cbranch_execz .LBB0_1034
	v_cmp_lt_u32_e32 vcc, s88, v14
	s_and_saveexec_b64 s[26:27], vcc
	s_xor_b64 s[46:47], exec, s[26:27]
	s_cbranch_execz .LBB0_1031
	s_movk_i32 s26, 0x47f
	v_cmp_lt_u32_e32 vcc, s26, v14
	s_and_saveexec_b64 s[26:27], vcc
	s_xor_b64 s[58:59], exec, s[26:27]
	s_cbranch_execz .LBB0_1028
	s_movk_i32 s26, 0x4bf
	v_cmp_lt_u32_e32 vcc, s26, v14
	s_and_saveexec_b64 s[26:27], vcc
	s_xor_b64 s[26:27], exec, s[26:27]
	s_cbranch_execz .LBB0_1025
	s_movk_i32 s28, 0x4ff
	v_cmp_lt_u32_e32 vcc, s28, v14
	s_and_saveexec_b64 s[28:29], vcc
	s_xor_b64 s[60:61], exec, s[28:29]
	s_cbranch_execz .LBB0_1022
	v_mul_f32_e32 v6, 0xbfb8aa3b, v6
	v_mul_f32_e32 v7, 0xbfb8aa3b, v7
	v_mul_f32_e32 v4, 0xbfb8aa3b, v4
	v_mul_f32_e32 v0, 0xbfb8aa3b, v16
	v_mul_f32_e32 v8, 0xbfb8aa3b, v17
	v_mul_f32_e32 v9, 0xbfb8aa3b, v10
	v_mul_f32_e32 v10, 0xbfb8aa3b, v11
	v_exp_f32_e32 v6, v6
	v_exp_f32_e32 v7, v7
	v_exp_f32_e32 v4, v4
	v_mul_f32_e32 v5, 0xbfb8aa3b, v5
	v_exp_f32_e32 v0, v0
	v_exp_f32_e32 v8, v8
	v_exp_f32_e32 v9, v9
	v_exp_f32_e32 v10, v10
	v_exp_f32_e32 v5, v5
	v_add_f32_e32 v6, 1.0, v6
	v_add_f32_e32 v7, 1.0, v7
	v_add_f32_e32 v4, 1.0, v4
	v_lshlrev_b64 v[2:3], 9, v[2:3]
	v_add_f32_e32 v0, 1.0, v0
	v_add_f32_e32 v8, 1.0, v8
	v_add_f32_e32 v9, 1.0, v9
	v_add_f32_e32 v10, 1.0, v10
	v_rcp_f32_e32 v6, v6
	v_rcp_f32_e32 v7, v7
	v_rcp_f32_e32 v11, v4
	v_add_f32_e32 v4, 1.0, v5
	v_lshl_add_u64 v[2:3], s[14:15], 0, v[2:3]
	v_rcp_f32_e32 v0, v0
	v_rcp_f32_e32 v8, v8
	v_rcp_f32_e32 v9, v9
	v_rcp_f32_e32 v10, v10
	v_rcp_f32_e32 v12, v4
	v_cvt_pk_bf16_f32 v4, v0, v8
	v_cvt_pk_bf16_f32 v5, v9, v10
	v_cvt_pk_bf16_f32 v6, v6, v7
	v_cvt_pk_bf16_f32 v7, v11, v12
	v_lshl_add_u64 v[2:3], v[14:15], 1, v[2:3]
	global_store_dwordx4 v[2:3], v[4:7], off offset:-2304
